# k28 plus loop-head/tile-init SALU placed after the first load segment's ds_reads (reads issue first after the barrier)
# baseline (speedup 1.0000x reference)
.Lprio_done:
	v_add_u32_e32 v170, 0x10000, v157
	ds_read_b128 v[128:131], v170
	ds_read_b128 v[132:135], v170 offset:1024
	ds_read_b128 v[136:139], v170 offset:2048
	ds_read_b128 v[140:143], v170 offset:3072
	ds_read_b128 v[166:169], v170 offset:16384
	ds_read_b128 v[176:179], v170 offset:17408
	ds_read_b128 v[180:183], v170 offset:18432
	ds_read_b128 v[184:187], v170 offset:19456
	s_add_i32 m0, s37, 0xc000
	ds_read_b128 v[188:191], v242
	ds_read_b128 v[192:195], v242 offset:1024
	ds_read_b128 v[196:199], v242 offset:2048
	ds_read_b128 v[200:203], v242 offset:3072
	ds_read_b128 v[204:207], v242 offset:4096
	ds_read_b128 v[208:211], v242 offset:5120
	ds_read_b128 v[212:215], v242 offset:6144
	ds_read_b128 v[216:219], v242 offset:7168
	s_add_u32 s0, s90, 0x80
	s_addc_u32 s1, s91, 0
	s_add_u32 s11, s2, 0x100
	s_addc_u32 s24, s3, 0
	s_mov_b32 s2, 0
	s_add_i32 s90, s2, 2
	s_add_u32 s82, s0, 0x80
	s_addc_u32 s3, s1, 0
	s_cmp_eq_u32 s62, s2
	s_cselect_b32 s3, s23, s3
	s_cselect_b32 s2, s22, s82
	s_cselect_b32 vcc_hi, s13, s24
	s_cselect_b32 vcc_lo, s12, s11
	v_add_u32_e32 v232, s26, v150
	v_add_u32_e32 v233, s26, v154
	v_add_u32_e32 v234, s58, v148
	v_add_u32_e32 v235, s58, v152
	global_load_lds_dwordx4 v160, s[0:1]
	s_add_i32 m0, s37, 0xe000
	s_nop 0
	global_load_lds_dwordx4 v162, s[0:1]
	s_waitcnt vmcnt(8) lgkmcnt(0)
	s_barrier
	v_mfma_f32_16x16x32_bf16 v[124:127], v[128:131], v[188:191], 0
	v_mfma_f32_16x16x32_bf16 v[120:123], v[136:139], v[188:191], 0
	v_mfma_f32_16x16x32_bf16 v[108:111], v[128:131], v[196:199], 0
	v_mfma_f32_16x16x32_bf16 v[104:107], v[136:139], v[196:199], 0
	v_mfma_f32_16x16x32_bf16 v[92:95], v[128:131], v[204:207], 0
	v_mfma_f32_16x16x32_bf16 v[88:91], v[136:139], v[204:207], 0
	v_mfma_f32_16x16x32_bf16 v[76:79], v[128:131], v[212:215], 0
	v_mfma_f32_16x16x32_bf16 v[72:75], v[136:139], v[212:215], 0
	v_mfma_f32_16x16x32_bf16 v[124:127], v[132:135], v[192:195], v[124:127]
	v_mfma_f32_16x16x32_bf16 v[120:123], v[140:143], v[192:195], v[120:123]
	v_mfma_f32_16x16x32_bf16 v[108:111], v[132:135], v[200:203], v[108:111]
	v_mfma_f32_16x16x32_bf16 v[104:107], v[140:143], v[200:203], v[104:107]
	v_mfma_f32_16x16x32_bf16 v[92:95], v[132:135], v[208:211], v[92:95]
	v_mfma_f32_16x16x32_bf16 v[88:91], v[140:143], v[208:211], v[88:91]
	v_mfma_f32_16x16x32_bf16 v[76:79], v[132:135], v[216:219], v[76:79]
	v_mfma_f32_16x16x32_bf16 v[72:75], v[140:143], v[216:219], v[72:75]
	v_mfma_f32_16x16x32_bf16 v[116:119], v[166:169], v[188:191], 0
	v_mfma_f32_16x16x32_bf16 v[112:115], v[180:183], v[188:191], 0
	v_mfma_f32_16x16x32_bf16 v[100:103], v[166:169], v[196:199], 0
	v_mfma_f32_16x16x32_bf16 v[96:99], v[180:183], v[196:199], 0
	v_mfma_f32_16x16x32_bf16 v[84:87], v[166:169], v[204:207], 0
	v_mfma_f32_16x16x32_bf16 v[80:83], v[180:183], v[204:207], 0
	v_mfma_f32_16x16x32_bf16 v[68:71], v[166:169], v[212:215], 0
	v_mfma_f32_16x16x32_bf16 v[64:67], v[180:183], v[212:215], 0
	v_mfma_f32_16x16x32_bf16 v[116:119], v[176:179], v[192:195], v[116:119]
	v_mfma_f32_16x16x32_bf16 v[112:115], v[184:187], v[192:195], v[112:115]
	v_mfma_f32_16x16x32_bf16 v[100:103], v[176:179], v[200:203], v[100:103]
	v_mfma_f32_16x16x32_bf16 v[96:99], v[184:187], v[200:203], v[96:99]
	v_mfma_f32_16x16x32_bf16 v[84:87], v[176:179], v[208:211], v[84:87]
	v_mfma_f32_16x16x32_bf16 v[80:83], v[184:187], v[208:211], v[80:83]
	v_mfma_f32_16x16x32_bf16 v[68:71], v[176:179], v[216:219], v[68:71]
	v_mfma_f32_16x16x32_bf16 v[64:67], v[184:187], v[216:219], v[64:67]
	s_barrier
	s_add_i32 m0, s36, 0x10000
	ds_read_b128 v[188:191], v242 offset:16384
	ds_read_b128 v[192:195], v242 offset:17408
	ds_read_b128 v[196:199], v242 offset:18432
	ds_read_b128 v[200:203], v242 offset:19456
	ds_read_b128 v[204:207], v242 offset:20480
	ds_read_b128 v[208:211], v242 offset:21504
	ds_read_b128 v[212:215], v242 offset:22528
	ds_read_b128 v[216:219], v242 offset:23552
	global_load_lds_dwordx4 v150, vcc
	s_add_i32 m0, s36, 0x12000
	s_nop 0
	global_load_lds_dwordx4 v154, vcc
	s_add_i32 m0, s36, 0x14000
	s_nop 0
	global_load_lds_dwordx4 v232, vcc
	s_add_i32 m0, s36, 0x16000
	s_nop 0
	global_load_lds_dwordx4 v233, vcc
	s_mov_b32 m0, s37
	s_nop 0
	global_load_lds_dwordx4 v148, s[2:3]
	s_mov_b32 m0, s42
	s_nop 0
	global_load_lds_dwordx4 v152, s[2:3]
	s_waitcnt vmcnt(8) lgkmcnt(0)
	s_barrier
	v_mfma_f32_16x16x32_bf16 v[60:63], v[128:131], v[188:191], 0
	v_mfma_f32_16x16x32_bf16 v[56:59], v[136:139], v[188:191], 0
	v_mfma_f32_16x16x32_bf16 v[44:47], v[128:131], v[196:199], 0
	v_mfma_f32_16x16x32_bf16 v[40:43], v[136:139], v[196:199], 0
	v_mfma_f32_16x16x32_bf16 v[28:31], v[128:131], v[204:207], 0
	v_mfma_f32_16x16x32_bf16 v[24:27], v[136:139], v[204:207], 0
	v_mfma_f32_16x16x32_bf16 v[12:15], v[128:131], v[212:215], 0
	v_mfma_f32_16x16x32_bf16 v[8:11], v[136:139], v[212:215], 0
	v_mfma_f32_16x16x32_bf16 v[60:63], v[132:135], v[192:195], v[60:63]
	v_mfma_f32_16x16x32_bf16 v[56:59], v[140:143], v[192:195], v[56:59]
	v_mfma_f32_16x16x32_bf16 v[44:47], v[132:135], v[200:203], v[44:47]
	v_mfma_f32_16x16x32_bf16 v[40:43], v[140:143], v[200:203], v[40:43]
	v_mfma_f32_16x16x32_bf16 v[28:31], v[132:135], v[208:211], v[28:31]
	v_mfma_f32_16x16x32_bf16 v[24:27], v[140:143], v[208:211], v[24:27]
	v_mfma_f32_16x16x32_bf16 v[12:15], v[132:135], v[216:219], v[12:15]
	v_mfma_f32_16x16x32_bf16 v[8:11], v[140:143], v[216:219], v[8:11]
	v_mfma_f32_16x16x32_bf16 v[52:55], v[166:169], v[188:191], 0
	v_mfma_f32_16x16x32_bf16 v[48:51], v[180:183], v[188:191], 0
	v_mfma_f32_16x16x32_bf16 v[36:39], v[166:169], v[196:199], 0
	v_mfma_f32_16x16x32_bf16 v[32:35], v[180:183], v[196:199], 0
	v_mfma_f32_16x16x32_bf16 v[20:23], v[166:169], v[204:207], 0
	v_mfma_f32_16x16x32_bf16 v[16:19], v[180:183], v[204:207], 0
	v_mfma_f32_16x16x32_bf16 v[4:7], v[166:169], v[212:215], 0
	v_mfma_f32_16x16x32_bf16 v[0:3], v[180:183], v[212:215], 0
	v_mfma_f32_16x16x32_bf16 v[52:55], v[176:179], v[192:195], v[52:55]
	v_mfma_f32_16x16x32_bf16 v[48:51], v[184:187], v[192:195], v[48:51]
	v_mfma_f32_16x16x32_bf16 v[36:39], v[176:179], v[200:203], v[36:39]
	v_mfma_f32_16x16x32_bf16 v[32:35], v[184:187], v[200:203], v[32:35]
	v_mfma_f32_16x16x32_bf16 v[20:23], v[176:179], v[208:211], v[20:23]
	v_mfma_f32_16x16x32_bf16 v[16:19], v[184:187], v[208:211], v[16:19]
	v_mfma_f32_16x16x32_bf16 v[4:7], v[176:179], v[216:219], v[4:7]
	v_mfma_f32_16x16x32_bf16 v[0:3], v[184:187], v[216:219], v[0:3]
	s_barrier
	ds_read_b128 v[128:131], v170 offset:32768
	ds_read_b128 v[132:135], v170 offset:33792
	ds_read_b128 v[136:139], v170 offset:34816
	ds_read_b128 v[140:143], v170 offset:35840
	ds_read_b128 v[166:169], v170 offset:49152
	ds_read_b128 v[176:179], v170 offset:50176
	ds_read_b128 v[180:183], v170 offset:51200
	ds_read_b128 v[184:187], v170 offset:52224
	s_mov_b32 m0, s43
	ds_read_b128 v[188:191], v242 offset:32768
	ds_read_b128 v[192:195], v242 offset:33792
	ds_read_b128 v[196:199], v242 offset:34816
	ds_read_b128 v[200:203], v242 offset:35840
	ds_read_b128 v[204:207], v242 offset:36864
	ds_read_b128 v[208:211], v242 offset:37888
	ds_read_b128 v[212:215], v242 offset:38912
	ds_read_b128 v[216:219], v242 offset:39936
	global_load_lds_dwordx4 v234, s[2:3]
	s_mov_b32 m0, s16
	s_nop 0
	global_load_lds_dwordx4 v235, s[2:3]
	s_waitcnt vmcnt(8) lgkmcnt(0)
	s_barrier
	v_mfma_f32_16x16x32_bf16 v[124:127], v[128:131], v[188:191], v[124:127]
	v_mfma_f32_16x16x32_bf16 v[120:123], v[136:139], v[188:191], v[120:123]
	v_mfma_f32_16x16x32_bf16 v[108:111], v[128:131], v[196:199], v[108:111]
	v_mfma_f32_16x16x32_bf16 v[104:107], v[136:139], v[196:199], v[104:107]
	v_mfma_f32_16x16x32_bf16 v[92:95], v[128:131], v[204:207], v[92:95]
	v_mfma_f32_16x16x32_bf16 v[88:91], v[136:139], v[204:207], v[88:91]
	v_mfma_f32_16x16x32_bf16 v[76:79], v[128:131], v[212:215], v[76:79]
	v_mfma_f32_16x16x32_bf16 v[72:75], v[136:139], v[212:215], v[72:75]
	v_mfma_f32_16x16x32_bf16 v[124:127], v[132:135], v[192:195], v[124:127]
	v_mfma_f32_16x16x32_bf16 v[120:123], v[140:143], v[192:195], v[120:123]
	v_mfma_f32_16x16x32_bf16 v[108:111], v[132:135], v[200:203], v[108:111]
	v_mfma_f32_16x16x32_bf16 v[104:107], v[140:143], v[200:203], v[104:107]
	v_mfma_f32_16x16x32_bf16 v[92:95], v[132:135], v[208:211], v[92:95]
	v_mfma_f32_16x16x32_bf16 v[88:91], v[140:143], v[208:211], v[88:91]
	v_mfma_f32_16x16x32_bf16 v[76:79], v[132:135], v[216:219], v[76:79]
	v_mfma_f32_16x16x32_bf16 v[72:75], v[140:143], v[216:219], v[72:75]
	v_mfma_f32_16x16x32_bf16 v[116:119], v[166:169], v[188:191], v[116:119]
	v_mfma_f32_16x16x32_bf16 v[112:115], v[180:183], v[188:191], v[112:115]
	v_mfma_f32_16x16x32_bf16 v[100:103], v[166:169], v[196:199], v[100:103]
	v_mfma_f32_16x16x32_bf16 v[96:99], v[180:183], v[196:199], v[96:99]
	v_mfma_f32_16x16x32_bf16 v[84:87], v[166:169], v[204:207], v[84:87]
	v_mfma_f32_16x16x32_bf16 v[80:83], v[180:183], v[204:207], v[80:83]
	v_mfma_f32_16x16x32_bf16 v[68:71], v[166:169], v[212:215], v[68:71]
	v_mfma_f32_16x16x32_bf16 v[64:67], v[180:183], v[212:215], v[64:67]
	v_mfma_f32_16x16x32_bf16 v[116:119], v[176:179], v[192:195], v[116:119]
	v_mfma_f32_16x16x32_bf16 v[112:115], v[184:187], v[192:195], v[112:115]
	v_mfma_f32_16x16x32_bf16 v[100:103], v[176:179], v[200:203], v[100:103]
	v_mfma_f32_16x16x32_bf16 v[96:99], v[184:187], v[200:203], v[96:99]
	v_mfma_f32_16x16x32_bf16 v[84:87], v[176:179], v[208:211], v[84:87]
	v_mfma_f32_16x16x32_bf16 v[80:83], v[184:187], v[208:211], v[80:83]
	v_mfma_f32_16x16x32_bf16 v[68:71], v[176:179], v[216:219], v[68:71]
	v_mfma_f32_16x16x32_bf16 v[64:67], v[184:187], v[216:219], v[64:67]
	s_barrier
	s_add_i32 m0, s36, 0x18000
	ds_read_b128 v[188:191], v242 offset:49152
	ds_read_b128 v[192:195], v242 offset:50176
	ds_read_b128 v[196:199], v242 offset:51200
	ds_read_b128 v[200:203], v242 offset:52224
	ds_read_b128 v[204:207], v242 offset:53248
	ds_read_b128 v[208:211], v242 offset:54272
	ds_read_b128 v[212:215], v242 offset:55296
	ds_read_b128 v[216:219], v242 offset:56320
	s_add_u32 vcc_lo, vcc_lo, 0x80
	s_addc_u32 vcc_hi, vcc_hi, 0
	global_load_lds_dwordx4 v150, vcc
	s_add_i32 m0, s36, 0x1a000
	s_add_u32 s2, s2, 0x80
	s_addc_u32 s3, s3, 0
	global_load_lds_dwordx4 v154, vcc
	s_add_i32 m0, s36, 0x1c000
	s_nop 0
	global_load_lds_dwordx4 v232, vcc
	s_add_i32 m0, s36, 0x1e000
	s_add_u32 s0, s0, 0x100
	s_addc_u32 s1, s1, 0
	global_load_lds_dwordx4 v233, vcc
	s_mov_b32 m0, s63
	s_add_u32 s11, s11, 0x100
	s_addc_u32 s24, s24, 0
	global_load_lds_dwordx4 v148, s[2:3]
	s_mov_b32 m0, s18
	s_nop 0
	global_load_lds_dwordx4 v152, s[2:3]
	s_waitcnt vmcnt(8) lgkmcnt(0)
	s_barrier
	v_mfma_f32_16x16x32_bf16 v[60:63], v[128:131], v[188:191], v[60:63]
	v_mfma_f32_16x16x32_bf16 v[56:59], v[136:139], v[188:191], v[56:59]
	v_mfma_f32_16x16x32_bf16 v[44:47], v[128:131], v[196:199], v[44:47]
	v_mfma_f32_16x16x32_bf16 v[40:43], v[136:139], v[196:199], v[40:43]
	v_mfma_f32_16x16x32_bf16 v[28:31], v[128:131], v[204:207], v[28:31]
	v_mfma_f32_16x16x32_bf16 v[24:27], v[136:139], v[204:207], v[24:27]
	v_mfma_f32_16x16x32_bf16 v[12:15], v[128:131], v[212:215], v[12:15]
	v_mfma_f32_16x16x32_bf16 v[8:11], v[136:139], v[212:215], v[8:11]
	v_mfma_f32_16x16x32_bf16 v[60:63], v[132:135], v[192:195], v[60:63]
	v_mfma_f32_16x16x32_bf16 v[56:59], v[140:143], v[192:195], v[56:59]
	v_mfma_f32_16x16x32_bf16 v[44:47], v[132:135], v[200:203], v[44:47]
	v_mfma_f32_16x16x32_bf16 v[40:43], v[140:143], v[200:203], v[40:43]
	v_mfma_f32_16x16x32_bf16 v[28:31], v[132:135], v[208:211], v[28:31]
	v_mfma_f32_16x16x32_bf16 v[24:27], v[140:143], v[208:211], v[24:27]
	v_mfma_f32_16x16x32_bf16 v[12:15], v[132:135], v[216:219], v[12:15]
	v_mfma_f32_16x16x32_bf16 v[8:11], v[140:143], v[216:219], v[8:11]
	v_mfma_f32_16x16x32_bf16 v[52:55], v[166:169], v[188:191], v[52:55]
	v_mfma_f32_16x16x32_bf16 v[48:51], v[180:183], v[188:191], v[48:51]
	v_mfma_f32_16x16x32_bf16 v[36:39], v[166:169], v[196:199], v[36:39]
	v_mfma_f32_16x16x32_bf16 v[32:35], v[180:183], v[196:199], v[32:35]
	v_mfma_f32_16x16x32_bf16 v[20:23], v[166:169], v[204:207], v[20:23]
	v_mfma_f32_16x16x32_bf16 v[16:19], v[180:183], v[204:207], v[16:19]
	v_mfma_f32_16x16x32_bf16 v[4:7], v[166:169], v[212:215], v[4:7]
	v_mfma_f32_16x16x32_bf16 v[0:3], v[180:183], v[212:215], v[0:3]
	v_mfma_f32_16x16x32_bf16 v[52:55], v[176:179], v[192:195], v[52:55]
	v_mfma_f32_16x16x32_bf16 v[48:51], v[184:187], v[192:195], v[48:51]
	v_mfma_f32_16x16x32_bf16 v[36:39], v[176:179], v[200:203], v[36:39]
	v_mfma_f32_16x16x32_bf16 v[32:35], v[184:187], v[200:203], v[32:35]
	v_mfma_f32_16x16x32_bf16 v[20:23], v[176:179], v[208:211], v[20:23]
	v_mfma_f32_16x16x32_bf16 v[16:19], v[184:187], v[208:211], v[16:19]
	v_mfma_f32_16x16x32_bf16 v[4:7], v[176:179], v[216:219], v[4:7]
	v_mfma_f32_16x16x32_bf16 v[0:3], v[184:187], v[216:219], v[0:3]
	s_barrier
	s_cmp_ge_u32 s90, s60
	s_mov_b32 s2, s90
	s_cbranch_scc1 .LBB0_297
.LBB0_295:
	ds_read_b128 v[128:131], v170
	ds_read_b128 v[132:135], v170 offset:1024
	ds_read_b128 v[136:139], v170 offset:2048
	ds_read_b128 v[140:143], v170 offset:3072
	ds_read_b128 v[166:169], v170 offset:16384
	ds_read_b128 v[176:179], v170 offset:17408
	ds_read_b128 v[180:183], v170 offset:18432
	ds_read_b128 v[184:187], v170 offset:19456
	s_add_i32 m0, s37, 0xc000
	ds_read_b128 v[188:191], v242
	ds_read_b128 v[192:195], v242 offset:1024
	ds_read_b128 v[196:199], v242 offset:2048
	ds_read_b128 v[200:203], v242 offset:3072
	ds_read_b128 v[204:207], v242 offset:4096
	ds_read_b128 v[208:211], v242 offset:5120
	ds_read_b128 v[212:215], v242 offset:6144
	ds_read_b128 v[216:219], v242 offset:7168
	s_add_i32 s90, s2, 2
	s_add_u32 s82, s0, 0x80
	s_addc_u32 s3, s1, 0
	s_cmp_eq_u32 s62, s2
	s_cselect_b32 s3, s23, s3
	s_cselect_b32 s2, s22, s82
	s_cselect_b32 vcc_hi, s13, s24
	s_cselect_b32 vcc_lo, s12, s11
	global_load_lds_dwordx4 v160, s[0:1]
	s_add_i32 m0, s37, 0xe000
	s_nop 0
	global_load_lds_dwordx4 v162, s[0:1]
	s_waitcnt vmcnt(8) lgkmcnt(0)
	s_barrier
	v_mfma_f32_16x16x32_bf16 v[124:127], v[128:131], v[188:191], v[124:127]
	v_mfma_f32_16x16x32_bf16 v[120:123], v[136:139], v[188:191], v[120:123]
	v_mfma_f32_16x16x32_bf16 v[108:111], v[128:131], v[196:199], v[108:111]
	v_mfma_f32_16x16x32_bf16 v[104:107], v[136:139], v[196:199], v[104:107]
	v_mfma_f32_16x16x32_bf16 v[92:95], v[128:131], v[204:207], v[92:95]
	v_mfma_f32_16x16x32_bf16 v[88:91], v[136:139], v[204:207], v[88:91]
	v_mfma_f32_16x16x32_bf16 v[76:79], v[128:131], v[212:215], v[76:79]
	v_mfma_f32_16x16x32_bf16 v[72:75], v[136:139], v[212:215], v[72:75]
	v_mfma_f32_16x16x32_bf16 v[124:127], v[132:135], v[192:195], v[124:127]
	v_mfma_f32_16x16x32_bf16 v[120:123], v[140:143], v[192:195], v[120:123]
	v_mfma_f32_16x16x32_bf16 v[108:111], v[132:135], v[200:203], v[108:111]
	v_mfma_f32_16x16x32_bf16 v[104:107], v[140:143], v[200:203], v[104:107]
	v_mfma_f32_16x16x32_bf16 v[92:95], v[132:135], v[208:211], v[92:95]
	v_mfma_f32_16x16x32_bf16 v[88:91], v[140:143], v[208:211], v[88:91]
	v_mfma_f32_16x16x32_bf16 v[76:79], v[132:135], v[216:219], v[76:79]
	v_mfma_f32_16x16x32_bf16 v[72:75], v[140:143], v[216:219], v[72:75]
	v_mfma_f32_16x16x32_bf16 v[116:119], v[166:169], v[188:191], v[116:119]
	v_mfma_f32_16x16x32_bf16 v[112:115], v[180:183], v[188:191], v[112:115]
	v_mfma_f32_16x16x32_bf16 v[100:103], v[166:169], v[196:199], v[100:103]
	v_mfma_f32_16x16x32_bf16 v[96:99], v[180:183], v[196:199], v[96:99]
	v_mfma_f32_16x16x32_bf16 v[84:87], v[166:169], v[204:207], v[84:87]
	v_mfma_f32_16x16x32_bf16 v[80:83], v[180:183], v[204:207], v[80:83]
	v_mfma_f32_16x16x32_bf16 v[68:71], v[166:169], v[212:215], v[68:71]
	v_mfma_f32_16x16x32_bf16 v[64:67], v[180:183], v[212:215], v[64:67]
	v_mfma_f32_16x16x32_bf16 v[116:119], v[176:179], v[192:195], v[116:119]
	v_mfma_f32_16x16x32_bf16 v[112:115], v[184:187], v[192:195], v[112:115]
	v_mfma_f32_16x16x32_bf16 v[100:103], v[176:179], v[200:203], v[100:103]
	v_mfma_f32_16x16x32_bf16 v[96:99], v[184:187], v[200:203], v[96:99]
	v_mfma_f32_16x16x32_bf16 v[84:87], v[176:179], v[208:211], v[84:87]
	v_mfma_f32_16x16x32_bf16 v[80:83], v[184:187], v[208:211], v[80:83]
	v_mfma_f32_16x16x32_bf16 v[68:71], v[176:179], v[216:219], v[68:71]
	v_mfma_f32_16x16x32_bf16 v[64:67], v[184:187], v[216:219], v[64:67]
	s_barrier
	s_add_i32 m0, s36, 0x10000
	ds_read_b128 v[188:191], v242 offset:16384
	ds_read_b128 v[192:195], v242 offset:17408
	ds_read_b128 v[196:199], v242 offset:18432
	ds_read_b128 v[200:203], v242 offset:19456
	ds_read_b128 v[204:207], v242 offset:20480
	ds_read_b128 v[208:211], v242 offset:21504
	ds_read_b128 v[212:215], v242 offset:22528
	ds_read_b128 v[216:219], v242 offset:23552
	global_load_lds_dwordx4 v150, vcc
	s_add_i32 m0, s36, 0x12000
	s_nop 0
	global_load_lds_dwordx4 v154, vcc
	s_add_i32 m0, s36, 0x14000
	s_nop 0
	global_load_lds_dwordx4 v232, vcc
	s_add_i32 m0, s36, 0x16000
	s_nop 0
	global_load_lds_dwordx4 v233, vcc
	s_mov_b32 m0, s37
	s_nop 0
	global_load_lds_dwordx4 v148, s[2:3]
	s_mov_b32 m0, s42
	s_nop 0
	global_load_lds_dwordx4 v152, s[2:3]
	s_waitcnt vmcnt(8) lgkmcnt(0)
	s_barrier
	v_mfma_f32_16x16x32_bf16 v[60:63], v[128:131], v[188:191], v[60:63]
	v_mfma_f32_16x16x32_bf16 v[56:59], v[136:139], v[188:191], v[56:59]
	v_mfma_f32_16x16x32_bf16 v[44:47], v[128:131], v[196:199], v[44:47]
	v_mfma_f32_16x16x32_bf16 v[40:43], v[136:139], v[196:199], v[40:43]
	v_mfma_f32_16x16x32_bf16 v[28:31], v[128:131], v[204:207], v[28:31]
	v_mfma_f32_16x16x32_bf16 v[24:27], v[136:139], v[204:207], v[24:27]
	v_mfma_f32_16x16x32_bf16 v[12:15], v[128:131], v[212:215], v[12:15]
	v_mfma_f32_16x16x32_bf16 v[8:11], v[136:139], v[212:215], v[8:11]
	v_mfma_f32_16x16x32_bf16 v[60:63], v[132:135], v[192:195], v[60:63]
	v_mfma_f32_16x16x32_bf16 v[56:59], v[140:143], v[192:195], v[56:59]
	v_mfma_f32_16x16x32_bf16 v[44:47], v[132:135], v[200:203], v[44:47]
	v_mfma_f32_16x16x32_bf16 v[40:43], v[140:143], v[200:203], v[40:43]
	v_mfma_f32_16x16x32_bf16 v[28:31], v[132:135], v[208:211], v[28:31]
	v_mfma_f32_16x16x32_bf16 v[24:27], v[140:143], v[208:211], v[24:27]
	v_mfma_f32_16x16x32_bf16 v[12:15], v[132:135], v[216:219], v[12:15]
	v_mfma_f32_16x16x32_bf16 v[8:11], v[140:143], v[216:219], v[8:11]
	v_mfma_f32_16x16x32_bf16 v[52:55], v[166:169], v[188:191], v[52:55]
	v_mfma_f32_16x16x32_bf16 v[48:51], v[180:183], v[188:191], v[48:51]
	v_mfma_f32_16x16x32_bf16 v[36:39], v[166:169], v[196:199], v[36:39]
	v_mfma_f32_16x16x32_bf16 v[32:35], v[180:183], v[196:199], v[32:35]
	v_mfma_f32_16x16x32_bf16 v[20:23], v[166:169], v[204:207], v[20:23]
	v_mfma_f32_16x16x32_bf16 v[16:19], v[180:183], v[204:207], v[16:19]
	v_mfma_f32_16x16x32_bf16 v[4:7], v[166:169], v[212:215], v[4:7]
	v_mfma_f32_16x16x32_bf16 v[0:3], v[180:183], v[212:215], v[0:3]
	v_mfma_f32_16x16x32_bf16 v[52:55], v[176:179], v[192:195], v[52:55]
	v_mfma_f32_16x16x32_bf16 v[48:51], v[184:187], v[192:195], v[48:51]
	v_mfma_f32_16x16x32_bf16 v[36:39], v[176:179], v[200:203], v[36:39]
	v_mfma_f32_16x16x32_bf16 v[32:35], v[184:187], v[200:203], v[32:35]
	v_mfma_f32_16x16x32_bf16 v[20:23], v[176:179], v[208:211], v[20:23]
	v_mfma_f32_16x16x32_bf16 v[16:19], v[184:187], v[208:211], v[16:19]
	v_mfma_f32_16x16x32_bf16 v[4:7], v[176:179], v[216:219], v[4:7]
	v_mfma_f32_16x16x32_bf16 v[0:3], v[184:187], v[216:219], v[0:3]
	s_barrier
	ds_read_b128 v[128:131], v170 offset:32768
	ds_read_b128 v[132:135], v170 offset:33792
	ds_read_b128 v[136:139], v170 offset:34816
	ds_read_b128 v[140:143], v170 offset:35840
	ds_read_b128 v[166:169], v170 offset:49152
	ds_read_b128 v[176:179], v170 offset:50176
	ds_read_b128 v[180:183], v170 offset:51200
	ds_read_b128 v[184:187], v170 offset:52224
	s_mov_b32 m0, s43
	ds_read_b128 v[188:191], v242 offset:32768
	ds_read_b128 v[192:195], v242 offset:33792
	ds_read_b128 v[196:199], v242 offset:34816
	ds_read_b128 v[200:203], v242 offset:35840
	ds_read_b128 v[204:207], v242 offset:36864
	ds_read_b128 v[208:211], v242 offset:37888
	ds_read_b128 v[212:215], v242 offset:38912
	ds_read_b128 v[216:219], v242 offset:39936
	global_load_lds_dwordx4 v234, s[2:3]
	s_mov_b32 m0, s16
	s_nop 0
	global_load_lds_dwordx4 v235, s[2:3]
	s_waitcnt vmcnt(8) lgkmcnt(0)
	s_barrier
	v_mfma_f32_16x16x32_bf16 v[124:127], v[128:131], v[188:191], v[124:127]
	v_mfma_f32_16x16x32_bf16 v[120:123], v[136:139], v[188:191], v[120:123]
	v_mfma_f32_16x16x32_bf16 v[108:111], v[128:131], v[196:199], v[108:111]
	v_mfma_f32_16x16x32_bf16 v[104:107], v[136:139], v[196:199], v[104:107]
	v_mfma_f32_16x16x32_bf16 v[92:95], v[128:131], v[204:207], v[92:95]
	v_mfma_f32_16x16x32_bf16 v[88:91], v[136:139], v[204:207], v[88:91]
	v_mfma_f32_16x16x32_bf16 v[76:79], v[128:131], v[212:215], v[76:79]
	v_mfma_f32_16x16x32_bf16 v[72:75], v[136:139], v[212:215], v[72:75]
	v_mfma_f32_16x16x32_bf16 v[124:127], v[132:135], v[192:195], v[124:127]
	v_mfma_f32_16x16x32_bf16 v[120:123], v[140:143], v[192:195], v[120:123]
	v_mfma_f32_16x16x32_bf16 v[108:111], v[132:135], v[200:203], v[108:111]
	v_mfma_f32_16x16x32_bf16 v[104:107], v[140:143], v[200:203], v[104:107]
	v_mfma_f32_16x16x32_bf16 v[92:95], v[132:135], v[208:211], v[92:95]
	v_mfma_f32_16x16x32_bf16 v[88:91], v[140:143], v[208:211], v[88:91]
	v_mfma_f32_16x16x32_bf16 v[76:79], v[132:135], v[216:219], v[76:79]
	v_mfma_f32_16x16x32_bf16 v[72:75], v[140:143], v[216:219], v[72:75]
	v_mfma_f32_16x16x32_bf16 v[116:119], v[166:169], v[188:191], v[116:119]
	v_mfma_f32_16x16x32_bf16 v[112:115], v[180:183], v[188:191], v[112:115]
	v_mfma_f32_16x16x32_bf16 v[100:103], v[166:169], v[196:199], v[100:103]
	v_mfma_f32_16x16x32_bf16 v[96:99], v[180:183], v[196:199], v[96:99]
	v_mfma_f32_16x16x32_bf16 v[84:87], v[166:169], v[204:207], v[84:87]
	v_mfma_f32_16x16x32_bf16 v[80:83], v[180:183], v[204:207], v[80:83]
	v_mfma_f32_16x16x32_bf16 v[68:71], v[166:169], v[212:215], v[68:71]
	v_mfma_f32_16x16x32_bf16 v[64:67], v[180:183], v[212:215], v[64:67]
	v_mfma_f32_16x16x32_bf16 v[116:119], v[176:179], v[192:195], v[116:119]
	v_mfma_f32_16x16x32_bf16 v[112:115], v[184:187], v[192:195], v[112:115]
	v_mfma_f32_16x16x32_bf16 v[100:103], v[176:179], v[200:203], v[100:103]
	v_mfma_f32_16x16x32_bf16 v[96:99], v[184:187], v[200:203], v[96:99]
	v_mfma_f32_16x16x32_bf16 v[84:87], v[176:179], v[208:211], v[84:87]
	v_mfma_f32_16x16x32_bf16 v[80:83], v[184:187], v[208:211], v[80:83]
	v_mfma_f32_16x16x32_bf16 v[68:71], v[176:179], v[216:219], v[68:71]
	v_mfma_f32_16x16x32_bf16 v[64:67], v[184:187], v[216:219], v[64:67]
	s_barrier
	s_add_i32 m0, s36, 0x18000
	ds_read_b128 v[188:191], v242 offset:49152
	ds_read_b128 v[192:195], v242 offset:50176
	ds_read_b128 v[196:199], v242 offset:51200
	ds_read_b128 v[200:203], v242 offset:52224
	ds_read_b128 v[204:207], v242 offset:53248
	ds_read_b128 v[208:211], v242 offset:54272
	ds_read_b128 v[212:215], v242 offset:55296
	ds_read_b128 v[216:219], v242 offset:56320
	s_add_u32 vcc_lo, vcc_lo, 0x80
	s_addc_u32 vcc_hi, vcc_hi, 0
	global_load_lds_dwordx4 v150, vcc
	s_add_i32 m0, s36, 0x1a000
	s_add_u32 s2, s2, 0x80
	s_addc_u32 s3, s3, 0
	global_load_lds_dwordx4 v154, vcc
	s_add_i32 m0, s36, 0x1c000
	s_nop 0
	global_load_lds_dwordx4 v232, vcc
	s_add_i32 m0, s36, 0x1e000
	s_add_u32 s0, s0, 0x100
	s_addc_u32 s1, s1, 0
	global_load_lds_dwordx4 v233, vcc
	s_mov_b32 m0, s63
	s_add_u32 s11, s11, 0x100
	s_addc_u32 s24, s24, 0
	global_load_lds_dwordx4 v148, s[2:3]
	s_mov_b32 m0, s18
	s_nop 0
	global_load_lds_dwordx4 v152, s[2:3]
	s_waitcnt vmcnt(8) lgkmcnt(0)
	s_barrier
	v_mfma_f32_16x16x32_bf16 v[60:63], v[128:131], v[188:191], v[60:63]
	v_mfma_f32_16x16x32_bf16 v[56:59], v[136:139], v[188:191], v[56:59]
	v_mfma_f32_16x16x32_bf16 v[44:47], v[128:131], v[196:199], v[44:47]
	v_mfma_f32_16x16x32_bf16 v[40:43], v[136:139], v[196:199], v[40:43]
	v_mfma_f32_16x16x32_bf16 v[28:31], v[128:131], v[204:207], v[28:31]
	v_mfma_f32_16x16x32_bf16 v[24:27], v[136:139], v[204:207], v[24:27]
	v_mfma_f32_16x16x32_bf16 v[12:15], v[128:131], v[212:215], v[12:15]
	v_mfma_f32_16x16x32_bf16 v[8:11], v[136:139], v[212:215], v[8:11]
	v_mfma_f32_16x16x32_bf16 v[60:63], v[132:135], v[192:195], v[60:63]
	v_mfma_f32_16x16x32_bf16 v[56:59], v[140:143], v[192:195], v[56:59]
	v_mfma_f32_16x16x32_bf16 v[44:47], v[132:135], v[200:203], v[44:47]
	v_mfma_f32_16x16x32_bf16 v[40:43], v[140:143], v[200:203], v[40:43]
	v_mfma_f32_16x16x32_bf16 v[28:31], v[132:135], v[208:211], v[28:31]
	v_mfma_f32_16x16x32_bf16 v[24:27], v[140:143], v[208:211], v[24:27]
	v_mfma_f32_16x16x32_bf16 v[12:15], v[132:135], v[216:219], v[12:15]
	v_mfma_f32_16x16x32_bf16 v[8:11], v[140:143], v[216:219], v[8:11]
	v_mfma_f32_16x16x32_bf16 v[52:55], v[166:169], v[188:191], v[52:55]
	v_mfma_f32_16x16x32_bf16 v[48:51], v[180:183], v[188:191], v[48:51]
	v_mfma_f32_16x16x32_bf16 v[36:39], v[166:169], v[196:199], v[36:39]
	v_mfma_f32_16x16x32_bf16 v[32:35], v[180:183], v[196:199], v[32:35]
	v_mfma_f32_16x16x32_bf16 v[20:23], v[166:169], v[204:207], v[20:23]
	v_mfma_f32_16x16x32_bf16 v[16:19], v[180:183], v[204:207], v[16:19]
	v_mfma_f32_16x16x32_bf16 v[4:7], v[166:169], v[212:215], v[4:7]
	v_mfma_f32_16x16x32_bf16 v[0:3], v[180:183], v[212:215], v[0:3]
	v_mfma_f32_16x16x32_bf16 v[52:55], v[176:179], v[192:195], v[52:55]
	v_mfma_f32_16x16x32_bf16 v[48:51], v[184:187], v[192:195], v[48:51]
	v_mfma_f32_16x16x32_bf16 v[36:39], v[176:179], v[200:203], v[36:39]
	v_mfma_f32_16x16x32_bf16 v[32:35], v[184:187], v[200:203], v[32:35]
	v_mfma_f32_16x16x32_bf16 v[20:23], v[176:179], v[208:211], v[20:23]
	v_mfma_f32_16x16x32_bf16 v[16:19], v[184:187], v[208:211], v[16:19]
	v_mfma_f32_16x16x32_bf16 v[4:7], v[176:179], v[216:219], v[4:7]
	v_mfma_f32_16x16x32_bf16 v[0:3], v[184:187], v[216:219], v[0:3]
	s_barrier
	s_cmp_ge_u32 s90, s60
	s_mov_b32 s2, s90
	s_cbranch_scc0 .LBB0_295
	s_branch .LBB0_297
